# grid barrier 5 split into arrive (end of GLA-output phase) and wait (first merge-unit epilogue)
# speedup vs baseline: 1.0100x; 1.0100x over previous
; DI unsigned xb_ld(unsigned* p)              { return __hip_atomic_load(p, __ATOMIC_RELAXED, __HIP_MEMORY_SCOPE_AGENT); }
; DI unsigned xb_add(unsigned* p, unsigned v) { return __hip_atomic_fetch_add(p, v, __ATOMIC_RELAXED, __HIP_MEMORY_SCOPE_AGENT); }
; #define XB_SPIN(cond, bar) do { unsigned _sp = 0; while (cond) { __builtin_amdgcn_s_sleep(1); \
;     if ((++_sp & 255u) == 0u) { if (xb_ld(&(bar)[XB_TMO])) break; if (_sp > XB_SPIN_CAP) { atomicAdd(&(bar)[XB_TMO], 1u); break; } } } } while (0)
; DI void xcd_barrier(const XcdBarrier& b) {
;     ...
;     if (threadIdx.x == 0) {
;         unsigned* bar = b.bar;
;         __builtin_amdgcn_s_waitcnt(0);
;         unsigned nloc = b.st[0], nx = b.st[1];
;         if (nloc == 0u) { xcd_barrier_complete(bar, b.x, nloc, nx); b.st[0] = nloc; b.st[1] = nx; }
;         const unsigned old = xb_add(&bar[XB_XSUB(b.x)], 1u);
;         const unsigned gen = old / nloc;
;         if (old + 1u == (gen + 1u) * nloc) {
;             __builtin_amdgcn_fence(__ATOMIC_RELEASE, "agent");
;             asm volatile("s_waitcnt vmcnt(0)" ::: "memory");
;             const unsigned og = xb_add(&bar[XB_TOP], 1u);
;             const unsigned tg = og / nx;
;             if (og + 1u == (tg + 1u) * nx) xb_add(&bar[XB_TOPGEN], 1u);
;             else XB_SPIN(xb_ld(&bar[XB_TOPGEN]) == tg, bar);
.LBB0_1145:
	s_waitcnt vmcnt(0) lgkmcnt(0)
	s_barrier
	v_cmp_eq_u32_e32 vcc, 0, v203
	s_and_saveexec_b64 s[4:5], vcc
	s_cbranch_execz .Lsb_arr_done
	v_mov_b32_e32 v0, 0x26100
	ds_read_b32 v1, v0
	ds_read_b32 v2, v0 offset:4
	s_waitcnt lgkmcnt(0)
	s_nop 0
	v_readfirstlane_b32 s6, v1
	v_readfirstlane_b32 s7, v2
	s_lshl_b32 s8, s33, 8
	s_add_u32 s8, s46, s8
	s_addc_u32 s9, s47, 0
	v_mov_b32_e32 v0, 0x1000
	v_mov_b32_e32 v1, 1
	global_atomic_add v2, v0, v1, s[8:9] offset:1024 sc0
	s_mov_b32 s101, 0
	s_waitcnt vmcnt(0)
	v_readfirstlane_b32 s10, v2
	s_mul_i32 s11, s6, 5
	s_add_i32 s10, s10, 1
	s_cmp_eq_u32 s10, s11
	s_cbranch_scc0 .Lsb_arr_done
	buffer_wbl2 sc1
	s_waitcnt vmcnt(0)
	v_mov_b32_e32 v0, 0x3000
	global_atomic_add v2, v0, v1, s[46:47] offset:1024 sc0
	s_mov_b32 s101, 1
	s_waitcnt vmcnt(0)
	v_readfirstlane_b32 s10, v2
	s_mul_i32 s11, s7, 5
	s_add_i32 s10, s10, 1
	s_cmp_eq_u32 s10, s11
	s_cbranch_scc0 .Lsb_arr_done
	v_mov_b32_e32 v0, 0x3100
	global_atomic_add v0, v1, s[46:47] offset:1024
	s_mov_b32 s101, 2
.Lsb_arr_done:
	s_or_b64 exec, exec, s[4:5]
	s_mov_b32 s100, 1
	v_mov_b32_e32 v10, v203
	s_waitcnt lgkmcnt(0)
	s_barrier
	s_load_dwordx2 s[8:9], s[0:1], 0xc8
	s_cmpk_lt_i32 s2, 0x100
	s_cselect_b64 s[12:13], -1, 0
	s_cmpk_gt_i32 s2, 0xff
	v_readfirstlane_b32 s11, v10
	s_cbranch_scc1 .LBB0_1200
	s_ashr_i32 s4, s2, 31
	s_lshr_b32 s4, s4, 29
	s_add_i32 s6, s2, s4
	s_and_b32 s4, s6, -8
	s_sub_i32 s7, s2, s4
	s_cmp_gt_i32 s7, -1
	s_cbranch_scc0 .LBB0_1201
	s_lshl_b32 s10, s7, 5
	s_cbranch_execz .LBB0_1202
	s_branch .LBB0_1203

; DI unsigned xb_ld(unsigned* p)              { return __hip_atomic_load(p, __ATOMIC_RELAXED, __HIP_MEMORY_SCOPE_AGENT); }
; DI unsigned xb_add(unsigned* p, unsigned v) { return __hip_atomic_fetch_add(p, v, __ATOMIC_RELAXED, __HIP_MEMORY_SCOPE_AGENT); }
; #define XB_SPIN(cond, bar) do { unsigned _sp = 0; while (cond) { __builtin_amdgcn_s_sleep(1); \
;     if ((++_sp & 255u) == 0u) { if (xb_ld(&(bar)[XB_TMO])) break; if (_sp > XB_SPIN_CAP) { atomicAdd(&(bar)[XB_TMO], 1u); break; } } } } while (0)
; DI void xcd_barrier(const XcdBarrier& b) {
;     ...
;         const unsigned old = xb_add(&bar[XB_XSUB(b.x)], 1u);
;         const unsigned gen = old / nloc;
;         if (old + 1u == (gen + 1u) * nloc) {
;             __builtin_amdgcn_fence(__ATOMIC_RELEASE, "agent");
;             asm volatile("s_waitcnt vmcnt(0)" ::: "memory");
;             const unsigned og = xb_add(&bar[XB_TOP], 1u);
;             const unsigned tg = og / nx;
;             if (og + 1u == (tg + 1u) * nx) xb_add(&bar[XB_TOPGEN], 1u);
;             else XB_SPIN(xb_ld(&bar[XB_TOPGEN]) == tg, bar);
;             __builtin_amdgcn_fence(__ATOMIC_ACQUIRE, "agent");
;             xb_add(&bar[XB_XGEN(b.x)], 1u);
;             asm volatile("s_waitcnt vmcnt(0)" ::: "memory");
;         } else {
;             XB_SPIN(xb_ld(&bar[XB_XGEN(b.x)]) == gen, bar);
;             __builtin_amdgcn_fence(__ATOMIC_ACQUIRE, "agent");
;             asm volatile("s_waitcnt vmcnt(0)" ::: "memory");
;         }
;     }
;     __syncthreads();
.LBB0_1230:
	s_cmp_eq_u32 s100, 0
	s_cbranch_scc1 .Lsb_done
	s_mov_b32 s100, 0
	v_cmp_eq_u32_e32 vcc, 0, v203
	s_and_saveexec_b64 s[40:41], vcc
	s_cbranch_execz .Lsb_join
	s_lshl_b32 s76, s33, 8
	s_add_u32 s76, s46, s76
	s_addc_u32 s77, s47, 0
	s_mov_b32 s42, 0
	s_cmp_eq_u32 s101, 2
	s_cbranch_scc1 .Lsb_lead_go
	s_cmp_eq_u32 s101, 1
	s_cbranch_scc1 .Lsb_lead_wait
	v_mov_b32_e32 v160, 0x2000
.Lsb_nl:
	global_load_dword v161, v160, s[76:77] offset:1024 sc1
	s_waitcnt vmcnt(0)
	v_readfirstlane_b32 s43, v161
	s_cmp_lg_u32 s43, 4
	s_cbranch_scc1 .Lsb_acq
	s_add_i32 s42, s42, 1
	s_cmp_lt_u32 s42, 0x800
	s_cbranch_scc0 .Lsb_acq
	s_sleep 1
	s_branch .Lsb_nl
.Lsb_lead_wait:
	v_mov_b32_e32 v160, 0x3100
.Lsb_lw:
	global_load_dword v161, v160, s[46:47] offset:1024 sc1
	s_waitcnt vmcnt(0)
	v_readfirstlane_b32 s43, v161
	s_cmp_lg_u32 s43, 4
	s_cbranch_scc1 .Lsb_lead_go
	s_add_i32 s42, s42, 1
	s_cmp_lt_u32 s42, 0x800
	s_cbranch_scc0 .Lsb_lead_go
	s_sleep 1
	s_branch .Lsb_lw
.Lsb_lead_go:
	buffer_inv sc1
	s_waitcnt vmcnt(0)
	v_mov_b32_e32 v160, 0x2000
	v_mov_b32_e32 v161, 1
	global_atomic_add v160, v161, s[76:77] offset:1024
	s_waitcnt vmcnt(0)
	s_branch .Lsb_join
.Lsb_acq:
	buffer_inv sc1
	s_waitcnt vmcnt(0)
.Lsb_join:
	s_or_b64 exec, exec, s[40:41]
	s_barrier
